# attention (FoX, DSA) output epilogues: adjacent-lane exchange by DPP quad_perm instead of ds_bpermute, on top of v18
# speedup vs baseline: 1.0021x; 1.0021x over previous
; #define LAS __attribute__((address_space(3)))
; __device__ __forceinline__ ArgsP get_args() { unsigned long long p = (unsigned long long)__builtin_amdgcn_kernarg_segment_ptr(); asm volatile("" : "+s"(p)); return (ArgsP)p; }
; __global__ void __launch_bounds__(NWAVES * 64, 2) mk_fwd(Args args) {
;     ...
;     if (IN(4)) { a = get_args();
;         if (MK_DBG & 8) { for (int u = 135168 / 4 + F.tid; u < LDS_BYTES / 4; u += NWAVES * 64) ((LAS unsigned*)F.lds)[u] = 0u; __syncthreads(); }
;         if (MK_DBG & 16) { for (int q = 0; q < 64; ++q) __builtin_amdgcn_s_sleep(64); }
;         if (MK_ATTN & 1) {
;             const float* biasK = (const float*)(a->ws + WS_BIASK);
;             float thr;
;             { const float* gq = (const float*)a->in[I_GQB]; const float* gk = (const float*)a->in[I_GKB];
;               float mq = fmaxf(fabsf(gq[F.lane]), fabsf(gq[F.lane + 64])), mk_ = fmaxf(fabsf(gk[F.lane]), fabsf(gk[F.lane + 64]));
; #pragma unroll
;               for (int o = 1; o < 64; o <<= 1) { mq = fmaxf(mq, __shfl_xor(mq, o)); mk_ = fmaxf(mk_, __shfl_xor(mk_, o)); }
;               thr = 2.0f * 11.313708499f * 1.03f * mq * mk_ + 96.0f; }
;     ...
;             { unsigned* qh = (unsigned*)(a->ws + WS_CTL) + CW_QFOX; int par = 0;
;               const int L0 = q_grab(F, qh, par);
.LBB0_512:
	v_readlane_b32 s2, v254, 11
	v_readlane_b32 s3, v254, 12
	s_cmp_lt_i32 s2, 5
	s_cselect_b64 s[2:3], -1, 0
	s_and_b64 s[0:1], s[2:3], s[0:1]
	v_writelane_b32 v254, s0, 15
	s_andn2_b64 vcc, exec, s[0:1]
	s_nop 0
	v_writelane_b32 v254, s1, 16
	v_writelane_b32 v254, s74, 17
	s_cbranch_vccnz .LBB0_1158
	s_mov_b64 s[4:5], s[56:57]
	s_load_dwordx4 s[0:3], s[4:5], 0x68
	v_lshlrev_b32_e32 v1, 2, v232
	v_writelane_b32 v254, s4, 18
	s_waitcnt lgkmcnt(0)
	global_load_dword v2, v1, s[0:1] offset:256
	global_load_dword v3, v1, s[0:1]
	global_load_dword v4, v1, s[2:3] offset:256
	global_load_dword v5, v1, s[2:3]
	v_mbcnt_lo_u32_b32 v1, -1, 0
	v_mbcnt_hi_u32_b32 v6, -1, v1
	v_and_b32_e32 v1, 64, v6
	v_xor_b32_e32 v7, 1, v6
	v_add_u32_e32 v13, 64, v1
	v_cmp_lt_i32_e32 vcc, v7, v13
	v_xor_b32_e32 v8, 2, v6
	v_xor_b32_e32 v9, 4, v6
	v_cndmask_b32_e32 v1, v6, v7, vcc
	v_lshlrev_b32_e32 v1, 2, v1
	v_cmp_lt_i32_e32 vcc, v8, v13
	v_xor_b32_e32 v10, 8, v6
	v_xor_b32_e32 v11, 16, v6
	v_cndmask_b32_e32 v7, v6, v8, vcc
	v_lshlrev_b32_e32 v213, 2, v7
	v_cmp_lt_i32_e32 vcc, v9, v13
	s_load_dwordx2 s[84:85], s[4:5], 0xd0
	v_xor_b32_e32 v12, 32, v6
	v_cndmask_b32_e32 v7, v6, v9, vcc
	v_lshlrev_b32_e32 v253, 2, v7
	v_cmp_lt_i32_e32 vcc, v10, v13
	s_waitcnt lgkmcnt(0)
	s_add_u32 s0, s84, 0x8000
	v_writelane_b32 v254, s5, 19
	v_cndmask_b32_e32 v7, v6, v10, vcc
	v_lshlrev_b32_e32 v210, 2, v7
	v_cmp_lt_i32_e32 vcc, v11, v13
	s_addc_u32 s1, s85, 0
	v_writelane_b32 v254, s0, 20
	v_cndmask_b32_e32 v7, v6, v11, vcc
	v_lshlrev_b32_e32 v7, 2, v7
	v_cmp_lt_i32_e32 vcc, v12, v13
	v_writelane_b32 v254, s1, 21
	s_waitcnt vmcnt(0)
	v_max_f32_e64 v2, |v2|, |v2|
	v_max_f32_e64 v3, |v3|, |v3|
	v_max_f32_e64 v4, |v4|, |v4|
	v_max_f32_e64 v5, |v5|, |v5|
	v_max_f32_e32 v2, v3, v2
	v_max_f32_e32 v3, v5, v4
	s_nop 1
	v_mov_b32_dpp v4, v2 quad_perm:[1,0,3,2] row_mask:0xf bank_mask:0xf
	s_nop 1
	v_mov_b32_dpp v5, v3 quad_perm:[1,0,3,2] row_mask:0xf bank_mask:0xf
	v_cndmask_b32_e32 v6, v6, v12, vcc
	v_lshlrev_b32_e32 v6, 2, v6
	s_waitcnt lgkmcnt(1)
	v_max_f32_e32 v4, v4, v4
	s_waitcnt lgkmcnt(0)
	v_max_f32_e32 v5, v5, v5
	v_max_f32_e32 v2, v2, v4
	v_max_f32_e32 v3, v3, v5
	ds_bpermute_b32 v4, v213, v2
	ds_bpermute_b32 v5, v213, v3
	s_waitcnt lgkmcnt(1)
	v_max_f32_e32 v4, v4, v4
	s_waitcnt lgkmcnt(0)
	v_max_f32_e32 v5, v5, v5
	v_max_f32_e32 v2, v2, v4
	v_max_f32_e32 v3, v3, v5
	ds_bpermute_b32 v4, v253, v2
	ds_bpermute_b32 v5, v253, v3
	s_waitcnt lgkmcnt(1)
	v_max_f32_e32 v4, v4, v4
	s_waitcnt lgkmcnt(0)
	v_max_f32_e32 v5, v5, v5
	v_max_f32_e32 v2, v2, v4
	v_max_f32_e32 v3, v3, v5
	ds_bpermute_b32 v4, v210, v2
	ds_bpermute_b32 v5, v210, v3
	s_waitcnt lgkmcnt(1)
	v_max_f32_e32 v4, v4, v4
	s_waitcnt lgkmcnt(0)
	v_max_f32_e32 v5, v5, v5
	v_max_f32_e32 v2, v2, v4
	v_max_f32_e32 v4, v3, v5
	ds_bpermute_b32 v3, v7, v2
	ds_bpermute_b32 v5, v7, v4
	s_waitcnt lgkmcnt(1)
	v_max_f32_e32 v3, v3, v3
	s_waitcnt lgkmcnt(0)
	v_max_f32_e32 v5, v5, v5
	v_max_f32_e32 v3, v2, v3
	v_max_f32_e32 v2, v4, v5
	ds_bpermute_b32 v5, v6, v3
	ds_bpermute_b32 v4, v6, v2
	s_mov_b64 s[0:1], exec
	v_readlane_b32 s2, v254, 8
	v_readlane_b32 s3, v254, 9
	s_and_b64 s[2:3], s[0:1], s[2:3]
	s_mov_b64 exec, s[2:3]
	s_cbranch_execz .LBB0_517
	s_mov_b64 s[4:5], exec
	v_mbcnt_lo_u32_b32 v6, s4, 0
	v_mbcnt_hi_u32_b32 v6, s5, v6
	v_cmp_eq_u32_e32 vcc, 0, v6
	s_and_saveexec_b64 s[2:3], vcc
	s_cbranch_execz .LBB0_516
	s_bcnt1_i32_b64 s4, s[4:5]
	v_mov_b32_e32 v8, s4
	v_readlane_b32 s4, v254, 20
	v_mov_b32_e32 v7, 0
	v_readlane_b32 s5, v254, 21
	s_nop 4
	global_atomic_add v7, v7, v8, s[4:5] sc0

; __device__ __forceinline__ unsigned cvtpk(float lo, float hi) { unsigned r; asm volatile("v_cvt_pk_bf16_f32 %0, %1, %2" : "=v"(r) : "v"(lo), "v"(hi)); return r; }
; #define SBAR() do { asm volatile("s_waitcnt vmcnt(0) lgkmcnt(0)" ::: "memory"); __syncthreads(); } while (0)
; #define SBAR() __builtin_amdgcn_sched_barrier(0)
; __device__ __forceinline__ int crow(int r, int hi) { return (r & 3) + 8 * (r >> 2) + 4 * hi; }
; #define SEAM_K0() do { if (QPRE) VMWN(8); else VMWN(0); SWRITE_HK(0); SBAR(); } while (0)
; template <int MODE>
; __device__ __forceinline__ void block(const Ref& cur, const Ref& nxt, char* lds, Seam& S) {
;     ...
;     SBAR(); SEAM_K0();
;     if (hie == 0) li_l[r32e] = l_reg; asm volatile("s_waitcnt lgkmcnt(0)" ::: "memory");
;     float rli[16];
; #pragma unroll
;     for (int r = 0; r < 16; ++r) rli[r] = __builtin_amdgcn_rcpf(li_l[crow(r, hie)]);
; #pragma unroll
;     for (int r = 0; r < 16; ++r) { bf16_t* orow = cur.O + qrow_off<MODE>(wid * QBLK + crow(r, hie));
; #pragma unroll
;         for (int d0 = 0; d0 < 4; ++d0) { const float v = o[d0][r] * rli[r];
;             const float vn = __shfl_xor(v, 1);
;             if ((r32e & 1) == 0) *(unsigned*)(orow + d0 * 32 + r32e) = cvtpk(v, vn); } }
.LBB0_570:
	v_and_b32_e32 v90, 31, v178
	v_bfe_u32 v5, v178, 5, 1
	s_waitcnt vmcnt(0)
	s_waitcnt vmcnt(1)
	ds_write_b128 v214, v[114:117] offset:32768
	s_waitcnt vmcnt(0)
	ds_write_b128 v214, v[118:121] offset:40960
	v_cmp_eq_u32_e32 vcc, 0, v5
	s_and_saveexec_b64 s[6:7], vcc
	v_lshl_add_u32 v3, v90, 2, s75
	ds_write_b32 v3, v2
	s_or_b64 exec, exec, s[6:7]
	s_waitcnt lgkmcnt(0)
	v_lshl_add_u32 v2, v5, 4, s75
	ds_read_b128 v[82:85], v2
	ds_read_b128 v[14:17], v2 offset:32
	ds_read_b128 v[10:13], v2 offset:64
	ds_read_b128 v[6:9], v2 offset:96
	v_and_b32_e32 v3, 1, v178
	s_waitcnt lgkmcnt(3)
	v_rcp_f32_e32 v82, v82
	v_lshl_or_b32 v2, v5, 2, s4
	v_cmp_eq_u32_e32 vcc, 0, v3
	v_mov_b32_e32 v3, v4
	v_lshlrev_b64 v[86:87], 12, v[2:3]
	v_mul_f32_e32 v3, v66, v82
	s_nop 1
	v_mov_b32_dpp v66, v3 quad_perm:[1,0,3,2] row_mask:0xf bank_mask:0xf
	v_lshl_add_u64 v[88:89], s[84:85], 0, v[86:87]
	v_lshlrev_b32_e32 v86, 1, v90
	v_mov_b32_e32 v87, v4
	v_lshl_add_u64 v[88:89], v[88:89], 0, v[86:87]
	s_and_saveexec_b64 s[6:7], vcc
	s_cbranch_execz .LBB0_574
	s_waitcnt lgkmcnt(0)
	v_cvt_pk_bf16_f32 v3, v3, v66
	global_store_dword v[88:89], v3, off
.LBB0_574:
	s_or_b64 exec, exec, s[6:7]
	v_mul_f32_e32 v3, v50, v82
	s_nop 1
	v_mov_b32_dpp v50, v3 quad_perm:[1,0,3,2] row_mask:0xf bank_mask:0xf
	s_and_saveexec_b64 s[6:7], vcc
	s_cbranch_execz .LBB0_576
	s_waitcnt lgkmcnt(0)
	v_cvt_pk_bf16_f32 v3, v3, v50
	global_store_dword v[88:89], v3, off offset:64
.LBB0_576:
	s_or_b64 exec, exec, s[6:7]
	v_mul_f32_e32 v3, v34, v82
	s_nop 1
	v_mov_b32_dpp v34, v3 quad_perm:[1,0,3,2] row_mask:0xf bank_mask:0xf
	s_and_saveexec_b64 s[6:7], vcc
	s_cbranch_execz .LBB0_578
	s_waitcnt lgkmcnt(0)
	v_cvt_pk_bf16_f32 v3, v3, v34
	global_store_dword v[88:89], v3, off offset:128
.LBB0_578:
	s_or_b64 exec, exec, s[6:7]
	v_mul_f32_e32 v3, v18, v82
	s_nop 1
	v_mov_b32_dpp v18, v3 quad_perm:[1,0,3,2] row_mask:0xf bank_mask:0xf
	s_and_saveexec_b64 s[6:7], vcc
	s_cbranch_execz .LBB0_580
	s_waitcnt lgkmcnt(0)
	v_cvt_pk_bf16_f32 v3, v3, v18
	global_store_dword v[88:89], v3, off offset:192
.LBB0_580:
	s_or_b64 exec, exec, s[6:7]
	v_rcp_f32_e32 v3, v83
	v_or_b32_e32 v82, 1, v2
	v_mov_b32_e32 v83, v4
	v_mov_b32_e32 v87, v4
	s_waitcnt lgkmcnt(0)
	v_mul_f32_e32 v18, v67, v3
	s_nop 1
	v_mov_b32_dpp v34, v18 quad_perm:[1,0,3,2] row_mask:0xf bank_mask:0xf
	v_lshlrev_b64 v[66:67], 12, v[82:83]
	v_lshl_add_u64 v[66:67], s[84:85], 0, v[66:67]
	v_lshl_add_u64 v[66:67], v[66:67], 0, v[86:87]
	s_and_saveexec_b64 s[6:7], vcc
	s_cbranch_execz .LBB0_582
	s_waitcnt lgkmcnt(0)
	v_cvt_pk_bf16_f32 v18, v18, v34
	global_store_dword v[66:67], v18, off
.LBB0_582:
	s_or_b64 exec, exec, s[6:7]
	v_mul_f32_e32 v18, v51, v3
	s_waitcnt lgkmcnt(0)
	s_nop 1
	v_mov_b32_dpp v34, v18 quad_perm:[1,0,3,2] row_mask:0xf bank_mask:0xf
	s_and_saveexec_b64 s[6:7], vcc
	s_cbranch_execz .LBB0_584
	s_waitcnt lgkmcnt(0)
	v_cvt_pk_bf16_f32 v18, v18, v34
	global_store_dword v[66:67], v18, off offset:64
.LBB0_584:
	s_or_b64 exec, exec, s[6:7]
	v_mul_f32_e32 v18, v35, v3
	s_waitcnt lgkmcnt(0)
	s_nop 1
	v_mov_b32_dpp v34, v18 quad_perm:[1,0,3,2] row_mask:0xf bank_mask:0xf
	s_and_saveexec_b64 s[6:7], vcc
	s_cbranch_execz .LBB0_586
	s_waitcnt lgkmcnt(0)
	v_cvt_pk_bf16_f32 v18, v18, v34
	global_store_dword v[66:67], v18, off offset:128
.LBB0_586:
	s_or_b64 exec, exec, s[6:7]
	v_mul_f32_e32 v3, v19, v3
	s_nop 1
	v_mov_b32_dpp v18, v3 quad_perm:[1,0,3,2] row_mask:0xf bank_mask:0xf
	s_and_saveexec_b64 s[6:7], vcc
	s_cbranch_execz .LBB0_588
	s_waitcnt lgkmcnt(0)
	v_cvt_pk_bf16_f32 v3, v3, v18
	global_store_dword v[66:67], v3, off offset:192
.LBB0_588:
	s_or_b64 exec, exec, s[6:7]
	v_rcp_f32_e32 v3, v84
	s_waitcnt lgkmcnt(0)
	v_or_b32_e32 v18, 2, v2
	v_mov_b32_e32 v19, v4
	v_lshlrev_b64 v[18:19], 12, v[18:19]
	v_mul_f32_e32 v34, v68, v3
	s_nop 1
	v_mov_b32_dpp v35, v34 quad_perm:[1,0,3,2] row_mask:0xf bank_mask:0xf
	v_lshl_add_u64 v[18:19], s[84:85], 0, v[18:19]
	v_mov_b32_e32 v87, v4
	v_lshl_add_u64 v[18:19], v[18:19], 0, v[86:87]
	s_and_saveexec_b64 s[6:7], vcc
	s_cbranch_execz .LBB0_590
	s_waitcnt lgkmcnt(0)
	v_cvt_pk_bf16_f32 v34, v34, v35
	global_store_dword v[18:19], v34, off
.LBB0_590:
	s_or_b64 exec, exec, s[6:7]
	v_mul_f32_e32 v34, v52, v3
	s_waitcnt lgkmcnt(0)
	s_nop 1
	v_mov_b32_dpp v35, v34 quad_perm:[1,0,3,2] row_mask:0xf bank_mask:0xf
	s_and_saveexec_b64 s[6:7], vcc
	s_cbranch_execz .LBB0_592
	s_waitcnt lgkmcnt(0)
	v_cvt_pk_bf16_f32 v34, v34, v35
	global_store_dword v[18:19], v34, off offset:64
.LBB0_592:
	s_or_b64 exec, exec, s[6:7]
	v_mul_f32_e32 v34, v36, v3
	s_waitcnt lgkmcnt(0)
	s_nop 1
	v_mov_b32_dpp v35, v34 quad_perm:[1,0,3,2] row_mask:0xf bank_mask:0xf
	s_and_saveexec_b64 s[6:7], vcc
	s_cbranch_execz .LBB0_594
	s_waitcnt lgkmcnt(0)
	v_cvt_pk_bf16_f32 v34, v34, v35
	global_store_dword v[18:19], v34, off offset:128
.LBB0_594:
	s_or_b64 exec, exec, s[6:7]
	v_mul_f32_e32 v3, v20, v3
	s_nop 1
	v_mov_b32_dpp v20, v3 quad_perm:[1,0,3,2] row_mask:0xf bank_mask:0xf
	s_and_saveexec_b64 s[6:7], vcc
	s_cbranch_execz .LBB0_596
	s_waitcnt lgkmcnt(0)
	v_cvt_pk_bf16_f32 v3, v3, v20
	global_store_dword v[18:19], v3, off offset:192
.LBB0_596:
	s_or_b64 exec, exec, s[6:7]
	v_rcp_f32_e32 v3, v85
	v_or_b32_e32 v18, 3, v2
	v_mov_b32_e32 v19, v4
	v_lshlrev_b64 v[18:19], 12, v[18:19]
	s_waitcnt lgkmcnt(0)
	v_mul_f32_e32 v20, v69, v3
	s_nop 1
	v_mov_b32_dpp v34, v20 quad_perm:[1,0,3,2] row_mask:0xf bank_mask:0xf
	v_lshl_add_u64 v[18:19], s[84:85], 0, v[18:19]
	v_mov_b32_e32 v87, v4
	v_lshl_add_u64 v[18:19], v[18:19], 0, v[86:87]
	s_and_saveexec_b64 s[6:7], vcc
	s_cbranch_execz .LBB0_598
	s_waitcnt lgkmcnt(0)
	v_cvt_pk_bf16_f32 v20, v20, v34
	global_store_dword v[18:19], v20, off
; __device__ __forceinline__ unsigned cvtpk(float lo, float hi) { unsigned r; asm volatile("v_cvt_pk_bf16_f32 %0, %1, %2" : "=v"(r) : "v"(lo), "v"(hi)); return r; }
; __device__ __forceinline__ int crow(int r, int hi) { return (r & 3) + 8 * (r >> 2) + 4 * hi; }
; template <int MODE>
; __device__ __forceinline__ void block(const Ref& cur, const Ref& nxt, char* lds, Seam& S) {
;     ...
;     for (int r = 0; r < 16; ++r) { bf16_t* orow = cur.O + qrow_off<MODE>(wid * QBLK + crow(r, hie));
; #pragma unroll
;         for (int d0 = 0; d0 < 4; ++d0) { const float v = o[d0][r] * rli[r];
;             const float vn = __shfl_xor(v, 1);
;             if ((r32e & 1) == 0) *(unsigned*)(orow + d0 * 32 + r32e) = cvtpk(v, vn); } }
.LBB0_598:
	s_or_b64 exec, exec, s[6:7]
	v_mul_f32_e32 v20, v53, v3
	s_waitcnt lgkmcnt(0)
	s_nop 1
	v_mov_b32_dpp v34, v20 quad_perm:[1,0,3,2] row_mask:0xf bank_mask:0xf
	s_and_saveexec_b64 s[6:7], vcc
	s_cbranch_execz .LBB0_600
	s_waitcnt lgkmcnt(0)
	v_cvt_pk_bf16_f32 v20, v20, v34
	global_store_dword v[18:19], v20, off offset:64
.LBB0_600:
	s_or_b64 exec, exec, s[6:7]
	v_mul_f32_e32 v20, v37, v3
	s_waitcnt lgkmcnt(0)
	s_nop 1
	v_mov_b32_dpp v34, v20 quad_perm:[1,0,3,2] row_mask:0xf bank_mask:0xf
	s_and_saveexec_b64 s[6:7], vcc
	s_cbranch_execz .LBB0_602
	s_waitcnt lgkmcnt(0)
	v_cvt_pk_bf16_f32 v20, v20, v34
	global_store_dword v[18:19], v20, off offset:128
.LBB0_602:
	s_or_b64 exec, exec, s[6:7]
	v_mul_f32_e32 v3, v21, v3
	s_nop 1
	v_mov_b32_dpp v20, v3 quad_perm:[1,0,3,2] row_mask:0xf bank_mask:0xf
	s_and_saveexec_b64 s[6:7], vcc
	s_cbranch_execz .LBB0_604
	s_waitcnt lgkmcnt(0)
	v_cvt_pk_bf16_f32 v3, v3, v20
	global_store_dword v[18:19], v3, off offset:192
.LBB0_604:
	s_or_b64 exec, exec, s[6:7]
	v_rcp_f32_e32 v3, v14
	v_or_b32_e32 v18, 8, v2
	v_mov_b32_e32 v19, v4
	v_lshlrev_b64 v[18:19], 12, v[18:19]
	v_mul_f32_e32 v14, v70, v3
	s_waitcnt lgkmcnt(0)
	s_nop 1
	v_mov_b32_dpp v20, v14 quad_perm:[1,0,3,2] row_mask:0xf bank_mask:0xf
	v_lshl_add_u64 v[18:19], s[84:85], 0, v[18:19]
	v_mov_b32_e32 v87, v4
	v_lshl_add_u64 v[18:19], v[18:19], 0, v[86:87]
	s_and_saveexec_b64 s[6:7], vcc
	s_cbranch_execz .LBB0_606
	s_waitcnt lgkmcnt(0)
	v_cvt_pk_bf16_f32 v14, v14, v20
	global_store_dword v[18:19], v14, off
.LBB0_606:
	s_or_b64 exec, exec, s[6:7]
	v_mul_f32_e32 v14, v54, v3
	s_waitcnt lgkmcnt(0)
	s_nop 1
	v_mov_b32_dpp v20, v14 quad_perm:[1,0,3,2] row_mask:0xf bank_mask:0xf
	s_and_saveexec_b64 s[6:7], vcc
	s_cbranch_execz .LBB0_608
	s_waitcnt lgkmcnt(0)
	v_cvt_pk_bf16_f32 v14, v14, v20
	global_store_dword v[18:19], v14, off offset:64
.LBB0_608:
	s_or_b64 exec, exec, s[6:7]
	v_mul_f32_e32 v14, v38, v3
	s_waitcnt lgkmcnt(0)
	s_nop 1
	v_mov_b32_dpp v20, v14 quad_perm:[1,0,3,2] row_mask:0xf bank_mask:0xf
	s_and_saveexec_b64 s[6:7], vcc
	s_cbranch_execz .LBB0_610
	s_waitcnt lgkmcnt(0)
	v_cvt_pk_bf16_f32 v14, v14, v20
	global_store_dword v[18:19], v14, off offset:128
.LBB0_610:
	s_or_b64 exec, exec, s[6:7]
	v_mul_f32_e32 v3, v22, v3
	s_nop 1
	v_mov_b32_dpp v14, v3 quad_perm:[1,0,3,2] row_mask:0xf bank_mask:0xf
	s_and_saveexec_b64 s[6:7], vcc
	s_cbranch_execz .LBB0_612
	s_waitcnt lgkmcnt(0)
	v_cvt_pk_bf16_f32 v3, v3, v14
	global_store_dword v[18:19], v3, off offset:192
.LBB0_612:
	s_or_b64 exec, exec, s[6:7]
	v_rcp_f32_e32 v3, v15
	s_waitcnt lgkmcnt(0)
	v_or_b32_e32 v14, 9, v2
	v_mov_b32_e32 v15, v4
	v_lshlrev_b64 v[14:15], 12, v[14:15]
	v_mul_f32_e32 v18, v71, v3
	s_nop 1
	v_mov_b32_dpp v19, v18 quad_perm:[1,0,3,2] row_mask:0xf bank_mask:0xf
	v_lshl_add_u64 v[14:15], s[84:85], 0, v[14:15]
	v_mov_b32_e32 v87, v4
	v_lshl_add_u64 v[14:15], v[14:15], 0, v[86:87]
	s_and_saveexec_b64 s[6:7], vcc
	s_cbranch_execz .LBB0_614
	s_waitcnt lgkmcnt(0)
	v_cvt_pk_bf16_f32 v18, v18, v19
	global_store_dword v[14:15], v18, off
.LBB0_614:
	s_or_b64 exec, exec, s[6:7]
	v_mul_f32_e32 v18, v55, v3
	s_waitcnt lgkmcnt(0)
	s_nop 1
	v_mov_b32_dpp v19, v18 quad_perm:[1,0,3,2] row_mask:0xf bank_mask:0xf
	s_and_saveexec_b64 s[6:7], vcc
	s_cbranch_execz .LBB0_616
	s_waitcnt lgkmcnt(0)
	v_cvt_pk_bf16_f32 v18, v18, v19
	global_store_dword v[14:15], v18, off offset:64
.LBB0_616:
	s_or_b64 exec, exec, s[6:7]
	v_mul_f32_e32 v18, v39, v3
	s_waitcnt lgkmcnt(0)
	s_nop 1
	v_mov_b32_dpp v19, v18 quad_perm:[1,0,3,2] row_mask:0xf bank_mask:0xf
	s_and_saveexec_b64 s[6:7], vcc
	s_cbranch_execz .LBB0_618
	s_waitcnt lgkmcnt(0)
	v_cvt_pk_bf16_f32 v18, v18, v19
	global_store_dword v[14:15], v18, off offset:128
.LBB0_618:
	s_or_b64 exec, exec, s[6:7]
	v_mul_f32_e32 v3, v23, v3
	s_nop 1
	v_mov_b32_dpp v18, v3 quad_perm:[1,0,3,2] row_mask:0xf bank_mask:0xf
	s_and_saveexec_b64 s[6:7], vcc
	s_cbranch_execz .LBB0_620
	s_waitcnt lgkmcnt(0)
	v_cvt_pk_bf16_f32 v3, v3, v18
	global_store_dword v[14:15], v3, off offset:192
.LBB0_620:
	s_or_b64 exec, exec, s[6:7]
	v_rcp_f32_e32 v3, v16
	v_or_b32_e32 v14, 10, v2
	v_mov_b32_e32 v15, v4
	v_lshlrev_b64 v[14:15], 12, v[14:15]
	v_mul_f32_e32 v16, v72, v3
	s_waitcnt lgkmcnt(0)
	s_nop 1
	v_mov_b32_dpp v18, v16 quad_perm:[1,0,3,2] row_mask:0xf bank_mask:0xf
	v_lshl_add_u64 v[14:15], s[84:85], 0, v[14:15]
	v_mov_b32_e32 v87, v4
	v_lshl_add_u64 v[14:15], v[14:15], 0, v[86:87]
	s_and_saveexec_b64 s[6:7], vcc
	s_cbranch_execz .LBB0_622
	s_waitcnt lgkmcnt(0)
	v_cvt_pk_bf16_f32 v16, v16, v18
	global_store_dword v[14:15], v16, off
.LBB0_622:
	s_or_b64 exec, exec, s[6:7]
	v_mul_f32_e32 v16, v56, v3
	s_waitcnt lgkmcnt(0)
	s_nop 1
	v_mov_b32_dpp v18, v16 quad_perm:[1,0,3,2] row_mask:0xf bank_mask:0xf
	s_and_saveexec_b64 s[6:7], vcc
	s_cbranch_execz .LBB0_624
	s_waitcnt lgkmcnt(0)
	v_cvt_pk_bf16_f32 v16, v16, v18
	global_store_dword v[14:15], v16, off offset:64
.LBB0_624:
	s_or_b64 exec, exec, s[6:7]
	v_mul_f32_e32 v16, v40, v3
	s_waitcnt lgkmcnt(0)
	s_nop 1
	v_mov_b32_dpp v18, v16 quad_perm:[1,0,3,2] row_mask:0xf bank_mask:0xf
	s_and_saveexec_b64 s[6:7], vcc
	s_cbranch_execz .LBB0_626
	s_waitcnt lgkmcnt(0)
	v_cvt_pk_bf16_f32 v16, v16, v18
	global_store_dword v[14:15], v16, off offset:128
.LBB0_626:
	s_or_b64 exec, exec, s[6:7]
	v_mul_f32_e32 v3, v24, v3
	s_nop 1
	v_mov_b32_dpp v16, v3 quad_perm:[1,0,3,2] row_mask:0xf bank_mask:0xf
	s_and_saveexec_b64 s[6:7], vcc
	s_cbranch_execz .LBB0_628
	s_waitcnt lgkmcnt(0)
	v_cvt_pk_bf16_f32 v3, v3, v16
	global_store_dword v[14:15], v3, off offset:192
; __device__ __forceinline__ unsigned cvtpk(float lo, float hi) { unsigned r; asm volatile("v_cvt_pk_bf16_f32 %0, %1, %2" : "=v"(r) : "v"(lo), "v"(hi)); return r; }
; __device__ __forceinline__ int crow(int r, int hi) { return (r & 3) + 8 * (r >> 2) + 4 * hi; }
; template <int MODE>
; __device__ __forceinline__ void block(const Ref& cur, const Ref& nxt, char* lds, Seam& S) {
;     ...
;     for (int r = 0; r < 16; ++r) { bf16_t* orow = cur.O + qrow_off<MODE>(wid * QBLK + crow(r, hie));
; #pragma unroll
;         for (int d0 = 0; d0 < 4; ++d0) { const float v = o[d0][r] * rli[r];
;             const float vn = __shfl_xor(v, 1);
;             if ((r32e & 1) == 0) *(unsigned*)(orow + d0 * 32 + r32e) = cvtpk(v, vn); } }
.LBB0_628:
	s_or_b64 exec, exec, s[6:7]
	v_rcp_f32_e32 v3, v17
	v_or_b32_e32 v14, 11, v2
	v_mov_b32_e32 v15, v4
	v_lshlrev_b64 v[14:15], 12, v[14:15]
	s_waitcnt lgkmcnt(0)
	v_mul_f32_e32 v16, v73, v3
	s_nop 1
	v_mov_b32_dpp v17, v16 quad_perm:[1,0,3,2] row_mask:0xf bank_mask:0xf
	v_lshl_add_u64 v[14:15], s[84:85], 0, v[14:15]
	v_mov_b32_e32 v87, v4
	v_lshl_add_u64 v[14:15], v[14:15], 0, v[86:87]
	s_and_saveexec_b64 s[6:7], vcc
	s_cbranch_execz .LBB0_630
	s_waitcnt lgkmcnt(0)
	v_cvt_pk_bf16_f32 v16, v16, v17
	global_store_dword v[14:15], v16, off
.LBB0_630:
	s_or_b64 exec, exec, s[6:7]
	v_mul_f32_e32 v16, v57, v3
	s_waitcnt lgkmcnt(0)
	s_nop 1
	v_mov_b32_dpp v17, v16 quad_perm:[1,0,3,2] row_mask:0xf bank_mask:0xf
	s_and_saveexec_b64 s[6:7], vcc
	s_cbranch_execz .LBB0_632
	s_waitcnt lgkmcnt(0)
	v_cvt_pk_bf16_f32 v16, v16, v17
	global_store_dword v[14:15], v16, off offset:64
.LBB0_632:
	s_or_b64 exec, exec, s[6:7]
	v_mul_f32_e32 v16, v41, v3
	s_waitcnt lgkmcnt(0)
	s_nop 1
	v_mov_b32_dpp v17, v16 quad_perm:[1,0,3,2] row_mask:0xf bank_mask:0xf
	s_and_saveexec_b64 s[6:7], vcc
	s_cbranch_execz .LBB0_634
	s_waitcnt lgkmcnt(0)
	v_cvt_pk_bf16_f32 v16, v16, v17
	global_store_dword v[14:15], v16, off offset:128
.LBB0_634:
	s_or_b64 exec, exec, s[6:7]
	v_mul_f32_e32 v3, v25, v3
	s_nop 1
	v_mov_b32_dpp v16, v3 quad_perm:[1,0,3,2] row_mask:0xf bank_mask:0xf
	s_and_saveexec_b64 s[6:7], vcc
	s_cbranch_execz .LBB0_636
	s_waitcnt lgkmcnt(0)
	v_cvt_pk_bf16_f32 v3, v3, v16
	global_store_dword v[14:15], v3, off offset:192
.LBB0_636:
	s_or_b64 exec, exec, s[6:7]
	v_rcp_f32_e32 v3, v10
	v_or_b32_e32 v14, 16, v2
	v_mov_b32_e32 v15, v4
	v_lshlrev_b64 v[14:15], 12, v[14:15]
	v_mul_f32_e32 v10, v74, v3
	s_waitcnt lgkmcnt(0)
	s_nop 1
	v_mov_b32_dpp v16, v10 quad_perm:[1,0,3,2] row_mask:0xf bank_mask:0xf
	v_lshl_add_u64 v[14:15], s[84:85], 0, v[14:15]
	v_mov_b32_e32 v87, v4
	v_lshl_add_u64 v[14:15], v[14:15], 0, v[86:87]
	s_and_saveexec_b64 s[6:7], vcc
	s_cbranch_execz .LBB0_638
	s_waitcnt lgkmcnt(0)
	v_cvt_pk_bf16_f32 v10, v10, v16
	global_store_dword v[14:15], v10, off
.LBB0_638:
	s_or_b64 exec, exec, s[6:7]
	v_mul_f32_e32 v10, v58, v3
	s_waitcnt lgkmcnt(0)
	s_nop 1
	v_mov_b32_dpp v16, v10 quad_perm:[1,0,3,2] row_mask:0xf bank_mask:0xf
	s_and_saveexec_b64 s[6:7], vcc
	s_cbranch_execz .LBB0_640
	s_waitcnt lgkmcnt(0)
	v_cvt_pk_bf16_f32 v10, v10, v16
	global_store_dword v[14:15], v10, off offset:64
.LBB0_640:
	s_or_b64 exec, exec, s[6:7]
	v_mul_f32_e32 v10, v42, v3
	s_waitcnt lgkmcnt(0)
	s_nop 1
	v_mov_b32_dpp v16, v10 quad_perm:[1,0,3,2] row_mask:0xf bank_mask:0xf
	s_and_saveexec_b64 s[6:7], vcc
	s_cbranch_execz .LBB0_642
	s_waitcnt lgkmcnt(0)
	v_cvt_pk_bf16_f32 v10, v10, v16
	global_store_dword v[14:15], v10, off offset:128
.LBB0_642:
	s_or_b64 exec, exec, s[6:7]
	v_mul_f32_e32 v3, v26, v3
	s_nop 1
	v_mov_b32_dpp v10, v3 quad_perm:[1,0,3,2] row_mask:0xf bank_mask:0xf
	s_and_saveexec_b64 s[6:7], vcc
	s_cbranch_execz .LBB0_644
	s_waitcnt lgkmcnt(0)
	v_cvt_pk_bf16_f32 v3, v3, v10
	global_store_dword v[14:15], v3, off offset:192
.LBB0_644:
	s_or_b64 exec, exec, s[6:7]
	v_rcp_f32_e32 v3, v11
	s_waitcnt lgkmcnt(0)
	v_or_b32_e32 v10, 17, v2
	v_mov_b32_e32 v11, v4
	v_lshlrev_b64 v[10:11], 12, v[10:11]
	v_mul_f32_e32 v14, v75, v3
	s_nop 1
	v_mov_b32_dpp v15, v14 quad_perm:[1,0,3,2] row_mask:0xf bank_mask:0xf
	v_lshl_add_u64 v[10:11], s[84:85], 0, v[10:11]
	v_mov_b32_e32 v87, v4
	v_lshl_add_u64 v[10:11], v[10:11], 0, v[86:87]
	s_and_saveexec_b64 s[6:7], vcc
	s_cbranch_execz .LBB0_646
	s_waitcnt lgkmcnt(0)
	v_cvt_pk_bf16_f32 v14, v14, v15
	global_store_dword v[10:11], v14, off
.LBB0_646:
	s_or_b64 exec, exec, s[6:7]
	v_mul_f32_e32 v14, v59, v3
	s_waitcnt lgkmcnt(0)
	s_nop 1
	v_mov_b32_dpp v15, v14 quad_perm:[1,0,3,2] row_mask:0xf bank_mask:0xf
	s_and_saveexec_b64 s[6:7], vcc
	s_cbranch_execz .LBB0_648
	s_waitcnt lgkmcnt(0)
	v_cvt_pk_bf16_f32 v14, v14, v15
	global_store_dword v[10:11], v14, off offset:64
.LBB0_648:
	s_or_b64 exec, exec, s[6:7]
	v_mul_f32_e32 v14, v43, v3
	s_waitcnt lgkmcnt(0)
	s_nop 1
	v_mov_b32_dpp v15, v14 quad_perm:[1,0,3,2] row_mask:0xf bank_mask:0xf
	s_and_saveexec_b64 s[6:7], vcc
	s_cbranch_execz .LBB0_650
	s_waitcnt lgkmcnt(0)
	v_cvt_pk_bf16_f32 v14, v14, v15
	global_store_dword v[10:11], v14, off offset:128
.LBB0_650:
	s_or_b64 exec, exec, s[6:7]
	v_mul_f32_e32 v3, v27, v3
	s_nop 1
	v_mov_b32_dpp v14, v3 quad_perm:[1,0,3,2] row_mask:0xf bank_mask:0xf
	s_and_saveexec_b64 s[6:7], vcc
	s_cbranch_execz .LBB0_652
	s_waitcnt lgkmcnt(0)
	v_cvt_pk_bf16_f32 v3, v3, v14
	global_store_dword v[10:11], v3, off offset:192
.LBB0_652:
	s_or_b64 exec, exec, s[6:7]
	v_rcp_f32_e32 v3, v12
	v_or_b32_e32 v10, 18, v2
	v_mov_b32_e32 v11, v4
	v_lshlrev_b64 v[10:11], 12, v[10:11]
	v_mul_f32_e32 v12, v76, v3
	s_waitcnt lgkmcnt(0)
	s_nop 1
	v_mov_b32_dpp v14, v12 quad_perm:[1,0,3,2] row_mask:0xf bank_mask:0xf
	v_lshl_add_u64 v[10:11], s[84:85], 0, v[10:11]
	v_mov_b32_e32 v87, v4
	v_lshl_add_u64 v[10:11], v[10:11], 0, v[86:87]
	s_and_saveexec_b64 s[6:7], vcc
	s_cbranch_execz .LBB0_654
	s_waitcnt lgkmcnt(0)
	v_cvt_pk_bf16_f32 v12, v12, v14
	global_store_dword v[10:11], v12, off
.LBB0_654:
	s_or_b64 exec, exec, s[6:7]
	v_mul_f32_e32 v12, v60, v3
	s_waitcnt lgkmcnt(0)
	s_nop 1
	v_mov_b32_dpp v14, v12 quad_perm:[1,0,3,2] row_mask:0xf bank_mask:0xf
	s_and_saveexec_b64 s[6:7], vcc
	s_cbranch_execz .LBB0_656
	s_waitcnt lgkmcnt(0)
	v_cvt_pk_bf16_f32 v12, v12, v14
	global_store_dword v[10:11], v12, off offset:64
.LBB0_656:
	s_or_b64 exec, exec, s[6:7]
	v_mul_f32_e32 v12, v44, v3
	s_waitcnt lgkmcnt(0)
	s_nop 1
	v_mov_b32_dpp v14, v12 quad_perm:[1,0,3,2] row_mask:0xf bank_mask:0xf
	s_and_saveexec_b64 s[6:7], vcc
	s_cbranch_execz .LBB0_658
	s_waitcnt lgkmcnt(0)
	v_cvt_pk_bf16_f32 v12, v12, v14
	global_store_dword v[10:11], v12, off offset:128
; __device__ __forceinline__ unsigned cvtpk(float lo, float hi) { unsigned r; asm volatile("v_cvt_pk_bf16_f32 %0, %1, %2" : "=v"(r) : "v"(lo), "v"(hi)); return r; }
; __device__ __forceinline__ int crow(int r, int hi) { return (r & 3) + 8 * (r >> 2) + 4 * hi; }
; template <int MODE>
; __device__ __forceinline__ void block(const Ref& cur, const Ref& nxt, char* lds, Seam& S) {
;     ...
;     for (int r = 0; r < 16; ++r) { bf16_t* orow = cur.O + qrow_off<MODE>(wid * QBLK + crow(r, hie));
; #pragma unroll
;         for (int d0 = 0; d0 < 4; ++d0) { const float v = o[d0][r] * rli[r];
;             const float vn = __shfl_xor(v, 1);
;             if ((r32e & 1) == 0) *(unsigned*)(orow + d0 * 32 + r32e) = cvtpk(v, vn); } }
.LBB0_658:
	s_or_b64 exec, exec, s[6:7]
	v_mul_f32_e32 v3, v28, v3
	s_nop 1
	v_mov_b32_dpp v12, v3 quad_perm:[1,0,3,2] row_mask:0xf bank_mask:0xf
	s_and_saveexec_b64 s[6:7], vcc
	s_cbranch_execz .LBB0_660
	s_waitcnt lgkmcnt(0)
	v_cvt_pk_bf16_f32 v3, v3, v12
	global_store_dword v[10:11], v3, off offset:192
.LBB0_660:
	s_or_b64 exec, exec, s[6:7]
	v_rcp_f32_e32 v3, v13
	v_or_b32_e32 v10, 19, v2
	v_mov_b32_e32 v11, v4
	v_lshlrev_b64 v[10:11], 12, v[10:11]
	s_waitcnt lgkmcnt(0)
	v_mul_f32_e32 v12, v77, v3
	s_nop 1
	v_mov_b32_dpp v13, v12 quad_perm:[1,0,3,2] row_mask:0xf bank_mask:0xf
	v_lshl_add_u64 v[10:11], s[84:85], 0, v[10:11]
	v_mov_b32_e32 v87, v4
	v_lshl_add_u64 v[10:11], v[10:11], 0, v[86:87]
	s_and_saveexec_b64 s[6:7], vcc
	s_cbranch_execz .LBB0_662
	s_waitcnt lgkmcnt(0)
	v_cvt_pk_bf16_f32 v12, v12, v13
	global_store_dword v[10:11], v12, off
.LBB0_662:
	s_or_b64 exec, exec, s[6:7]
	v_mul_f32_e32 v12, v61, v3
	s_waitcnt lgkmcnt(0)
	s_nop 1
	v_mov_b32_dpp v13, v12 quad_perm:[1,0,3,2] row_mask:0xf bank_mask:0xf
	s_and_saveexec_b64 s[6:7], vcc
	s_cbranch_execz .LBB0_664
	s_waitcnt lgkmcnt(0)
	v_cvt_pk_bf16_f32 v12, v12, v13
	global_store_dword v[10:11], v12, off offset:64
.LBB0_664:
	s_or_b64 exec, exec, s[6:7]
	v_mul_f32_e32 v12, v45, v3
	s_waitcnt lgkmcnt(0)
	s_nop 1
	v_mov_b32_dpp v13, v12 quad_perm:[1,0,3,2] row_mask:0xf bank_mask:0xf
	s_and_saveexec_b64 s[6:7], vcc
	s_cbranch_execz .LBB0_666
	s_waitcnt lgkmcnt(0)
	v_cvt_pk_bf16_f32 v12, v12, v13
	global_store_dword v[10:11], v12, off offset:128
.LBB0_666:
	s_or_b64 exec, exec, s[6:7]
	v_mul_f32_e32 v3, v29, v3
	s_nop 1
	v_mov_b32_dpp v12, v3 quad_perm:[1,0,3,2] row_mask:0xf bank_mask:0xf
	s_and_saveexec_b64 s[6:7], vcc
	s_cbranch_execz .LBB0_668
	s_waitcnt lgkmcnt(0)
	v_cvt_pk_bf16_f32 v3, v3, v12
	global_store_dword v[10:11], v3, off offset:192
.LBB0_668:
	s_or_b64 exec, exec, s[6:7]
	v_rcp_f32_e32 v3, v6
	v_or_b32_e32 v10, 24, v2
	v_mov_b32_e32 v11, v4
	v_lshlrev_b64 v[10:11], 12, v[10:11]
	v_mul_f32_e32 v6, v78, v3
	s_waitcnt lgkmcnt(0)
	s_nop 1
	v_mov_b32_dpp v12, v6 quad_perm:[1,0,3,2] row_mask:0xf bank_mask:0xf
	v_lshl_add_u64 v[10:11], s[84:85], 0, v[10:11]
	v_mov_b32_e32 v87, v4
	v_lshl_add_u64 v[10:11], v[10:11], 0, v[86:87]
	s_and_saveexec_b64 s[6:7], vcc
	s_cbranch_execz .LBB0_670
	s_waitcnt lgkmcnt(0)
	v_cvt_pk_bf16_f32 v6, v6, v12
	global_store_dword v[10:11], v6, off
.LBB0_670:
	s_or_b64 exec, exec, s[6:7]
	v_mul_f32_e32 v6, v62, v3
	s_waitcnt lgkmcnt(0)
	s_nop 1
	v_mov_b32_dpp v12, v6 quad_perm:[1,0,3,2] row_mask:0xf bank_mask:0xf
	s_and_saveexec_b64 s[6:7], vcc
	s_cbranch_execz .LBB0_672
	s_waitcnt lgkmcnt(0)
	v_cvt_pk_bf16_f32 v6, v6, v12
	global_store_dword v[10:11], v6, off offset:64
.LBB0_672:
	s_or_b64 exec, exec, s[6:7]
	v_mul_f32_e32 v6, v46, v3
	s_waitcnt lgkmcnt(0)
	s_nop 1
	v_mov_b32_dpp v12, v6 quad_perm:[1,0,3,2] row_mask:0xf bank_mask:0xf
	s_and_saveexec_b64 s[6:7], vcc
	s_cbranch_execz .LBB0_674
	s_waitcnt lgkmcnt(0)
	v_cvt_pk_bf16_f32 v6, v6, v12
	global_store_dword v[10:11], v6, off offset:128
.LBB0_674:
	s_or_b64 exec, exec, s[6:7]
	v_mul_f32_e32 v3, v30, v3
	s_nop 1
	v_mov_b32_dpp v6, v3 quad_perm:[1,0,3,2] row_mask:0xf bank_mask:0xf
	s_and_saveexec_b64 s[6:7], vcc
	s_cbranch_execz .LBB0_676
	s_waitcnt lgkmcnt(0)
	v_cvt_pk_bf16_f32 v3, v3, v6
	global_store_dword v[10:11], v3, off offset:192
.LBB0_676:
	s_or_b64 exec, exec, s[6:7]
	v_rcp_f32_e32 v3, v7
	s_waitcnt lgkmcnt(0)
	v_or_b32_e32 v6, 25, v2
	v_mov_b32_e32 v7, v4
	v_lshlrev_b64 v[6:7], 12, v[6:7]
	v_mul_f32_e32 v10, v79, v3
	s_nop 1
	v_mov_b32_dpp v11, v10 quad_perm:[1,0,3,2] row_mask:0xf bank_mask:0xf
	v_lshl_add_u64 v[6:7], s[84:85], 0, v[6:7]
	v_mov_b32_e32 v87, v4
	v_lshl_add_u64 v[6:7], v[6:7], 0, v[86:87]
	s_and_saveexec_b64 s[6:7], vcc
	s_cbranch_execz .LBB0_678
	s_waitcnt lgkmcnt(0)
	v_cvt_pk_bf16_f32 v10, v10, v11
	global_store_dword v[6:7], v10, off
; __device__ __forceinline__ unsigned cvtpk(float lo, float hi) { unsigned r; asm volatile("v_cvt_pk_bf16_f32 %0, %1, %2" : "=v"(r) : "v"(lo), "v"(hi)); return r; }
; __device__ __forceinline__ int crow(int r, int hi) { return (r & 3) + 8 * (r >> 2) + 4 * hi; }
; template <int MODE>
; __device__ __forceinline__ void block(const Ref& cur, const Ref& nxt, char* lds, Seam& S) {
;     ...
;     for (int r = 0; r < 16; ++r) { bf16_t* orow = cur.O + qrow_off<MODE>(wid * QBLK + crow(r, hie));
; #pragma unroll
;         for (int d0 = 0; d0 < 4; ++d0) { const float v = o[d0][r] * rli[r];
;             const float vn = __shfl_xor(v, 1);
;             if ((r32e & 1) == 0) *(unsigned*)(orow + d0 * 32 + r32e) = cvtpk(v, vn); } }
.LBB0_678:
	s_or_b64 exec, exec, s[6:7]
	v_mul_f32_e32 v10, v63, v3
	s_waitcnt lgkmcnt(0)
	s_nop 1
	v_mov_b32_dpp v11, v10 quad_perm:[1,0,3,2] row_mask:0xf bank_mask:0xf
	s_and_saveexec_b64 s[6:7], vcc
	s_cbranch_execz .LBB0_680
	s_waitcnt lgkmcnt(0)
	v_cvt_pk_bf16_f32 v10, v10, v11
	global_store_dword v[6:7], v10, off offset:64
.LBB0_680:
	s_or_b64 exec, exec, s[6:7]
	v_mul_f32_e32 v10, v47, v3
	s_waitcnt lgkmcnt(0)
	s_nop 1
	v_mov_b32_dpp v11, v10 quad_perm:[1,0,3,2] row_mask:0xf bank_mask:0xf
	s_and_saveexec_b64 s[6:7], vcc
	s_cbranch_execz .LBB0_682
	s_waitcnt lgkmcnt(0)
	v_cvt_pk_bf16_f32 v10, v10, v11
	global_store_dword v[6:7], v10, off offset:128
.LBB0_682:
	s_or_b64 exec, exec, s[6:7]
	v_mul_f32_e32 v3, v31, v3
	s_nop 1
	v_mov_b32_dpp v10, v3 quad_perm:[1,0,3,2] row_mask:0xf bank_mask:0xf
	s_and_saveexec_b64 s[6:7], vcc
	s_cbranch_execz .LBB0_684
	s_waitcnt lgkmcnt(0)
	v_cvt_pk_bf16_f32 v3, v3, v10
	global_store_dword v[6:7], v3, off offset:192
.LBB0_684:
	s_or_b64 exec, exec, s[6:7]
	v_rcp_f32_e32 v3, v8
	v_or_b32_e32 v6, 26, v2
	v_mov_b32_e32 v7, v4
	v_lshlrev_b64 v[6:7], 12, v[6:7]
	v_mul_f32_e32 v8, v80, v3
	s_waitcnt lgkmcnt(0)
	s_nop 1
	v_mov_b32_dpp v10, v8 quad_perm:[1,0,3,2] row_mask:0xf bank_mask:0xf
	v_lshl_add_u64 v[6:7], s[84:85], 0, v[6:7]
	v_mov_b32_e32 v87, v4
	v_lshl_add_u64 v[6:7], v[6:7], 0, v[86:87]
	s_and_saveexec_b64 s[6:7], vcc
	s_cbranch_execz .LBB0_686
	s_waitcnt lgkmcnt(0)
	v_cvt_pk_bf16_f32 v8, v8, v10
	global_store_dword v[6:7], v8, off
.LBB0_686:
	s_or_b64 exec, exec, s[6:7]
	v_mul_f32_e32 v8, v64, v3
	s_waitcnt lgkmcnt(0)
	s_nop 1
	v_mov_b32_dpp v10, v8 quad_perm:[1,0,3,2] row_mask:0xf bank_mask:0xf
	s_and_saveexec_b64 s[6:7], vcc
	s_cbranch_execz .LBB0_688
	s_waitcnt lgkmcnt(0)
	v_cvt_pk_bf16_f32 v8, v8, v10
	global_store_dword v[6:7], v8, off offset:64
.LBB0_688:
	s_or_b64 exec, exec, s[6:7]
	v_mul_f32_e32 v8, v48, v3
	s_waitcnt lgkmcnt(0)
	s_nop 1
	v_mov_b32_dpp v10, v8 quad_perm:[1,0,3,2] row_mask:0xf bank_mask:0xf
	s_and_saveexec_b64 s[6:7], vcc
	s_cbranch_execz .LBB0_690
	s_waitcnt lgkmcnt(0)
	v_cvt_pk_bf16_f32 v8, v8, v10
	global_store_dword v[6:7], v8, off offset:128
.LBB0_690:
	s_or_b64 exec, exec, s[6:7]
	v_mul_f32_e32 v3, v32, v3
	s_nop 1
	v_mov_b32_dpp v8, v3 quad_perm:[1,0,3,2] row_mask:0xf bank_mask:0xf
	s_and_saveexec_b64 s[6:7], vcc
	s_cbranch_execz .LBB0_692
	s_waitcnt lgkmcnt(0)
	v_cvt_pk_bf16_f32 v3, v3, v8
	global_store_dword v[6:7], v3, off offset:192
.LBB0_692:
	s_or_b64 exec, exec, s[6:7]
	v_rcp_f32_e32 v6, v9
	v_or_b32_e32 v2, 27, v2
	v_mov_b32_e32 v3, v4
	v_lshlrev_b64 v[2:3], 12, v[2:3]
	v_mul_f32_e32 v7, v81, v6
	s_waitcnt lgkmcnt(0)
	s_nop 1
	v_mov_b32_dpp v8, v7 quad_perm:[1,0,3,2] row_mask:0xf bank_mask:0xf
	v_lshl_add_u64 v[2:3], s[84:85], 0, v[2:3]
	v_mov_b32_e32 v87, v4
	v_lshl_add_u64 v[2:3], v[2:3], 0, v[86:87]
	s_and_saveexec_b64 s[6:7], vcc
	s_cbranch_execz .LBB0_694
	s_waitcnt lgkmcnt(0)
	v_cvt_pk_bf16_f32 v7, v7, v8
	global_store_dword v[2:3], v7, off
.LBB0_694:
	s_or_b64 exec, exec, s[6:7]
	v_mul_f32_e32 v7, v65, v6
	s_waitcnt lgkmcnt(0)
	s_nop 1
	v_mov_b32_dpp v8, v7 quad_perm:[1,0,3,2] row_mask:0xf bank_mask:0xf
	s_and_saveexec_b64 s[6:7], vcc
	s_cbranch_execz .LBB0_696
	s_waitcnt lgkmcnt(0)
	v_cvt_pk_bf16_f32 v7, v7, v8
	global_store_dword v[2:3], v7, off offset:64
.LBB0_696:
	s_or_b64 exec, exec, s[6:7]
	v_mul_f32_e32 v7, v49, v6
	s_waitcnt lgkmcnt(0)
	s_nop 1
	v_mov_b32_dpp v8, v7 quad_perm:[1,0,3,2] row_mask:0xf bank_mask:0xf
	s_and_saveexec_b64 s[6:7], vcc
	s_cbranch_execz .LBB0_698
	s_waitcnt lgkmcnt(0)
	v_cvt_pk_bf16_f32 v7, v7, v8
	global_store_dword v[2:3], v7, off offset:128
.LBB0_698:
	s_or_b64 exec, exec, s[6:7]
	v_mul_f32_e32 v6, v33, v6
	s_nop 1
	v_mov_b32_dpp v7, v6 quad_perm:[1,0,3,2] row_mask:0xf bank_mask:0xf
	s_and_saveexec_b64 s[6:7], vcc
	s_cbranch_execz .LBB0_700
	s_waitcnt lgkmcnt(0)
	v_cvt_pk_bf16_f32 v6, v6, v7
	global_store_dword v[2:3], v6, off offset:192

; __device__ __forceinline__ unsigned cvtpk(float lo, float hi) { unsigned r; asm volatile("v_cvt_pk_bf16_f32 %0, %1, %2" : "=v"(r) : "v"(lo), "v"(hi)); return r; }
; #define SBAR() do { asm volatile("s_waitcnt vmcnt(0) lgkmcnt(0)" ::: "memory"); __syncthreads(); } while (0)
; #define SBAR() __builtin_amdgcn_sched_barrier(0)
; __device__ __forceinline__ int crow(int r, int hi) { return (r & 3) + 8 * (r >> 2) + 4 * hi; }
; #define SEAM_K0() do { if (QPRE) VMWN(8); else VMWN(0); SWRITE_HK(0); SBAR(); } while (0)
; template <int MODE>
; __device__ __forceinline__ void block(const Ref& cur, const Ref& nxt, char* lds, Seam& S) {
;     ...
;     SBAR(); SEAM_K0();
;     if (hie == 0) li_l[r32e] = l_reg; asm volatile("s_waitcnt lgkmcnt(0)" ::: "memory");
;     float rli[16];
; #pragma unroll
;     for (int r = 0; r < 16; ++r) rli[r] = __builtin_amdgcn_rcpf(li_l[crow(r, hie)]);
; #pragma unroll
;     for (int r = 0; r < 16; ++r) { bf16_t* orow = cur.O + qrow_off<MODE>(wid * QBLK + crow(r, hie));
; #pragma unroll
;         for (int d0 = 0; d0 < 4; ++d0) { const float v = o[d0][r] * rli[r];
;             const float vn = __shfl_xor(v, 1);
;             if ((r32e & 1) == 0) *(unsigned*)(orow + d0 * 32 + r32e) = cvtpk(v, vn); } }
.LBB0_1254:
	s_waitcnt vmcnt(8)
	s_waitcnt vmcnt(9)
	ds_write_b128 v211, v[138:141] offset:32768
	s_waitcnt vmcnt(8)
	ds_write_b128 v211, v[142:145] offset:40960
	v_cmp_eq_u32_e32 vcc, 0, v129
	s_and_saveexec_b64 s[20:21], vcc
	v_lshl_add_u32 v2, v16, 2, s28
	ds_write_b32 v2, v1
	s_or_b64 exec, exec, s[20:21]
	s_waitcnt lgkmcnt(0)
	v_lshl_add_u32 v1, v129, 4, s28
	ds_read_b128 v[82:85], v1
	ds_read_b128 v[12:15], v1 offset:32
	ds_read_b128 v[8:11], v1 offset:64
	ds_read_b128 v[4:7], v1 offset:96
	v_and_b32_e32 v2, 64, v217
	s_waitcnt lgkmcnt(3)
	v_rcp_f32_e32 v82, v82
	v_xor_b32_e32 v1, 1, v217
	v_add_u32_e32 v2, 64, v2
	v_cmp_lt_i32_e32 vcc, v1, v2
	v_mul_f32_e32 v66, v66, v82
	s_lshl_b64 s[20:21], s[6:7], 12
	v_cndmask_b32_e32 v1, v217, v1, vcc
	v_lshlrev_b32_e32 v1, 2, v1
	s_nop 1
	v_mov_b32_dpp v86, v66 quad_perm:[1,0,3,2] row_mask:0xf bank_mask:0xf
	v_and_b32_e32 v2, 1, v17
	s_add_u32 s20, s18, s20
	v_cmp_eq_u32_e32 vcc, 0, v2
	s_addc_u32 s21, s19, s21
	v_lshlrev_b32_e32 v2, 10, v129
	v_lshl_add_u64 v[88:89], s[20:21], 0, v[2:3]
	v_lshlrev_b32_e32 v2, 1, v16
	v_lshl_add_u64 v[16:17], v[88:89], 0, v[2:3]
	s_and_saveexec_b64 s[20:21], vcc
	s_cbranch_execz .LBB0_1258
	s_waitcnt lgkmcnt(0)
	v_cvt_pk_bf16_f32 v66, v66, v86
	global_store_dword v[16:17], v66, off
.LBB0_1258:
	s_or_b64 exec, exec, s[20:21]
	v_mul_f32_e32 v50, v50, v82
	s_nop 1
	v_mov_b32_dpp v66, v50 quad_perm:[1,0,3,2] row_mask:0xf bank_mask:0xf
	s_and_saveexec_b64 s[20:21], vcc
	s_cbranch_execz .LBB0_1260
	s_waitcnt lgkmcnt(0)
	v_cvt_pk_bf16_f32 v50, v50, v66
	global_store_dword v[16:17], v50, off offset:64
.LBB0_1260:
	s_or_b64 exec, exec, s[20:21]
	v_mul_f32_e32 v34, v34, v82
	s_nop 1
	v_mov_b32_dpp v50, v34 quad_perm:[1,0,3,2] row_mask:0xf bank_mask:0xf
	s_and_saveexec_b64 s[20:21], vcc
	s_cbranch_execz .LBB0_1262
	s_waitcnt lgkmcnt(0)
	v_cvt_pk_bf16_f32 v34, v34, v50
	global_store_dword v[16:17], v34, off offset:128
.LBB0_1262:
	s_or_b64 exec, exec, s[20:21]
	v_mul_f32_e32 v18, v18, v82
	s_nop 1
	v_mov_b32_dpp v34, v18 quad_perm:[1,0,3,2] row_mask:0xf bank_mask:0xf
	s_and_saveexec_b64 s[20:21], vcc
	s_cbranch_execz .LBB0_1264
	s_waitcnt lgkmcnt(0)
	v_cvt_pk_bf16_f32 v18, v18, v34
	global_store_dword v[16:17], v18, off offset:192
.LBB0_1264:
	s_or_b64 exec, exec, s[20:21]
	v_rcp_f32_e32 v18, v83
	s_waitcnt lgkmcnt(0)
	v_mul_f32_e32 v34, v67, v18
	s_nop 1
	v_mov_b32_dpp v50, v34 quad_perm:[1,0,3,2] row_mask:0xf bank_mask:0xf
	s_and_saveexec_b64 s[20:21], vcc
	s_cbranch_execz .LBB0_1266
	s_waitcnt lgkmcnt(0)
	v_cvt_pk_bf16_f32 v34, v34, v50
	global_store_dword v[16:17], v34, off offset:256
.LBB0_1266:
	s_or_b64 exec, exec, s[20:21]
	v_mul_f32_e32 v34, v51, v18
	s_waitcnt lgkmcnt(0)
	s_nop 1
	v_mov_b32_dpp v50, v34 quad_perm:[1,0,3,2] row_mask:0xf bank_mask:0xf
	s_and_saveexec_b64 s[20:21], vcc
	s_cbranch_execz .LBB0_1268
	s_waitcnt lgkmcnt(0)
	v_cvt_pk_bf16_f32 v34, v34, v50
	global_store_dword v[16:17], v34, off offset:320
.LBB0_1268:
	s_or_b64 exec, exec, s[20:21]
	v_mul_f32_e32 v34, v35, v18
	s_nop 1
	v_mov_b32_dpp v35, v34 quad_perm:[1,0,3,2] row_mask:0xf bank_mask:0xf
	s_and_saveexec_b64 s[20:21], vcc
	s_cbranch_execz .LBB0_1270
	s_waitcnt lgkmcnt(0)
	v_cvt_pk_bf16_f32 v34, v34, v35
	global_store_dword v[16:17], v34, off offset:384
.LBB0_1270:
	s_or_b64 exec, exec, s[20:21]
	v_mul_f32_e32 v18, v19, v18
	s_nop 1
	v_mov_b32_dpp v19, v18 quad_perm:[1,0,3,2] row_mask:0xf bank_mask:0xf
	s_and_saveexec_b64 s[20:21], vcc
	s_cbranch_execz .LBB0_1272
	s_waitcnt lgkmcnt(0)
	v_cvt_pk_bf16_f32 v18, v18, v19
	global_store_dword v[16:17], v18, off offset:448
.LBB0_1272:
	s_or_b64 exec, exec, s[20:21]
	v_rcp_f32_e32 v18, v84
	s_waitcnt lgkmcnt(0)
	v_mul_f32_e32 v19, v68, v18
	s_nop 1
	v_mov_b32_dpp v34, v19 quad_perm:[1,0,3,2] row_mask:0xf bank_mask:0xf
	s_and_saveexec_b64 s[20:21], vcc
	s_cbranch_execz .LBB0_1274
	s_waitcnt lgkmcnt(0)
	v_cvt_pk_bf16_f32 v19, v19, v34
	global_store_dword v[16:17], v19, off offset:512
.LBB0_1274:
	s_or_b64 exec, exec, s[20:21]
	v_mul_f32_e32 v19, v52, v18
	s_waitcnt lgkmcnt(0)
	s_nop 1
	v_mov_b32_dpp v34, v19 quad_perm:[1,0,3,2] row_mask:0xf bank_mask:0xf
	s_and_saveexec_b64 s[20:21], vcc
	s_cbranch_execz .LBB0_1276
	s_waitcnt lgkmcnt(0)
	v_cvt_pk_bf16_f32 v19, v19, v34
	global_store_dword v[16:17], v19, off offset:576
.LBB0_1276:
	s_or_b64 exec, exec, s[20:21]
	v_mul_f32_e32 v19, v36, v18
	s_waitcnt lgkmcnt(0)
	s_nop 1
	v_mov_b32_dpp v34, v19 quad_perm:[1,0,3,2] row_mask:0xf bank_mask:0xf
	s_and_saveexec_b64 s[20:21], vcc
	s_cbranch_execz .LBB0_1278
	s_waitcnt lgkmcnt(0)
	v_cvt_pk_bf16_f32 v19, v19, v34
	global_store_dword v[16:17], v19, off offset:640
.LBB0_1278:
	s_or_b64 exec, exec, s[20:21]
	v_mul_f32_e32 v18, v20, v18
	s_nop 1
	v_mov_b32_dpp v19, v18 quad_perm:[1,0,3,2] row_mask:0xf bank_mask:0xf
	s_and_saveexec_b64 s[20:21], vcc
	s_cbranch_execz .LBB0_1280
	s_waitcnt lgkmcnt(0)
	v_cvt_pk_bf16_f32 v18, v18, v19
	global_store_dword v[16:17], v18, off offset:704
.LBB0_1280:
	s_or_b64 exec, exec, s[20:21]
	v_rcp_f32_e32 v18, v85
	s_waitcnt lgkmcnt(0)
	v_mul_f32_e32 v19, v69, v18
	s_nop 1
	v_mov_b32_dpp v20, v19 quad_perm:[1,0,3,2] row_mask:0xf bank_mask:0xf
	s_and_saveexec_b64 s[20:21], vcc
	s_cbranch_execz .LBB0_1282
	s_waitcnt lgkmcnt(0)
	v_cvt_pk_bf16_f32 v19, v19, v20
	global_store_dword v[16:17], v19, off offset:768
.LBB0_1282:
	s_or_b64 exec, exec, s[20:21]
	v_mul_f32_e32 v19, v53, v18
	s_waitcnt lgkmcnt(0)
	s_nop 1
	v_mov_b32_dpp v20, v19 quad_perm:[1,0,3,2] row_mask:0xf bank_mask:0xf
	s_and_saveexec_b64 s[20:21], vcc
	s_cbranch_execz .LBB0_1284
	s_waitcnt lgkmcnt(0)
	v_cvt_pk_bf16_f32 v19, v19, v20
	global_store_dword v[16:17], v19, off offset:832
; __device__ __forceinline__ unsigned cvtpk(float lo, float hi) { unsigned r; asm volatile("v_cvt_pk_bf16_f32 %0, %1, %2" : "=v"(r) : "v"(lo), "v"(hi)); return r; }
; __device__ __forceinline__ int crow(int r, int hi) { return (r & 3) + 8 * (r >> 2) + 4 * hi; }
; template <int MODE>
; __device__ __forceinline__ void block(const Ref& cur, const Ref& nxt, char* lds, Seam& S) {
;     ...
;     for (int r = 0; r < 16; ++r) { bf16_t* orow = cur.O + qrow_off<MODE>(wid * QBLK + crow(r, hie));
; #pragma unroll
;         for (int d0 = 0; d0 < 4; ++d0) { const float v = o[d0][r] * rli[r];
;             const float vn = __shfl_xor(v, 1);
;             if ((r32e & 1) == 0) *(unsigned*)(orow + d0 * 32 + r32e) = cvtpk(v, vn); } }
.LBB0_1284:
	s_or_b64 exec, exec, s[20:21]
	v_mul_f32_e32 v19, v37, v18
	s_waitcnt lgkmcnt(0)
	s_nop 1
	v_mov_b32_dpp v20, v19 quad_perm:[1,0,3,2] row_mask:0xf bank_mask:0xf
	s_and_saveexec_b64 s[20:21], vcc
	s_cbranch_execz .LBB0_1286
	s_waitcnt lgkmcnt(0)
	v_cvt_pk_bf16_f32 v19, v19, v20
	global_store_dword v[16:17], v19, off offset:896
.LBB0_1286:
	s_or_b64 exec, exec, s[20:21]
	v_mul_f32_e32 v18, v21, v18
	s_nop 1
	v_mov_b32_dpp v19, v18 quad_perm:[1,0,3,2] row_mask:0xf bank_mask:0xf
	s_and_saveexec_b64 s[20:21], vcc
	s_cbranch_execz .LBB0_1288
	s_waitcnt lgkmcnt(0)
	v_cvt_pk_bf16_f32 v18, v18, v19
	global_store_dword v[16:17], v18, off offset:960
.LBB0_1288:
	s_or_b64 exec, exec, s[20:21]
	v_rcp_f32_e32 v12, v12
	s_or_b32 s20, s6, 1
	s_mov_b32 s21, s7
	s_lshl_b64 s[20:21], s[20:21], 12
	s_waitcnt lgkmcnt(1)
	v_mul_f32_e32 v20, v70, v12
	s_nop 1
	v_mov_b32_dpp v21, v20 quad_perm:[1,0,3,2] row_mask:0xf bank_mask:0xf
	v_lshlrev_b32_e32 v16, 9, v129
	s_add_u32 s20, s18, s20
	s_addc_u32 s21, s19, s21
	v_lshlrev_b32_e32 v16, 1, v16
	v_mov_b32_e32 v17, v3
	s_waitcnt lgkmcnt(1)
	v_lshl_add_u64 v[18:19], s[20:21], 0, v[16:17]
	v_lshl_add_u64 v[18:19], v[18:19], 0, v[2:3]
	s_and_saveexec_b64 s[20:21], vcc
	s_cbranch_execz .LBB0_1290
	s_waitcnt lgkmcnt(0)
	v_cvt_pk_bf16_f32 v17, v20, v21
	global_store_dword v[18:19], v17, off
.LBB0_1290:
	s_or_b64 exec, exec, s[20:21]
	v_mul_f32_e32 v17, v54, v12
	s_nop 1
	v_mov_b32_dpp v20, v17 quad_perm:[1,0,3,2] row_mask:0xf bank_mask:0xf
	s_and_saveexec_b64 s[20:21], vcc
	s_cbranch_execz .LBB0_1292
	s_waitcnt lgkmcnt(0)
	v_cvt_pk_bf16_f32 v17, v17, v20
	global_store_dword v[18:19], v17, off offset:64
.LBB0_1292:
	s_or_b64 exec, exec, s[20:21]
	v_mul_f32_e32 v17, v38, v12
	s_waitcnt lgkmcnt(0)
	s_nop 1
	v_mov_b32_dpp v20, v17 quad_perm:[1,0,3,2] row_mask:0xf bank_mask:0xf
	s_and_saveexec_b64 s[20:21], vcc
	s_cbranch_execz .LBB0_1294
	s_waitcnt lgkmcnt(0)
	v_cvt_pk_bf16_f32 v17, v17, v20
	global_store_dword v[18:19], v17, off offset:128
.LBB0_1294:
	s_or_b64 exec, exec, s[20:21]
	v_mul_f32_e32 v12, v22, v12
	s_nop 1
	v_mov_b32_dpp v17, v12 quad_perm:[1,0,3,2] row_mask:0xf bank_mask:0xf
	s_and_saveexec_b64 s[20:21], vcc
	s_cbranch_execz .LBB0_1296
	s_waitcnt lgkmcnt(0)
	v_cvt_pk_bf16_f32 v12, v12, v17
	global_store_dword v[18:19], v12, off offset:192
.LBB0_1296:
	s_or_b64 exec, exec, s[20:21]
	v_rcp_f32_e32 v12, v13
	s_nop 0
	v_mul_f32_e32 v13, v71, v12
	s_waitcnt lgkmcnt(0)
	s_nop 1
	v_mov_b32_dpp v17, v13 quad_perm:[1,0,3,2] row_mask:0xf bank_mask:0xf
	s_and_saveexec_b64 s[20:21], vcc
	s_cbranch_execz .LBB0_1298
	s_waitcnt lgkmcnt(0)
	v_cvt_pk_bf16_f32 v13, v13, v17
	global_store_dword v[18:19], v13, off offset:256
.LBB0_1298:
	s_or_b64 exec, exec, s[20:21]
	v_mul_f32_e32 v13, v55, v12
	s_waitcnt lgkmcnt(0)
	s_nop 1
	v_mov_b32_dpp v17, v13 quad_perm:[1,0,3,2] row_mask:0xf bank_mask:0xf
	s_and_saveexec_b64 s[20:21], vcc
	s_cbranch_execz .LBB0_1300
	s_waitcnt lgkmcnt(0)
	v_cvt_pk_bf16_f32 v13, v13, v17
	global_store_dword v[18:19], v13, off offset:320
.LBB0_1300:
	s_or_b64 exec, exec, s[20:21]
	v_mul_f32_e32 v13, v39, v12
	s_waitcnt lgkmcnt(0)
	s_nop 1
	v_mov_b32_dpp v17, v13 quad_perm:[1,0,3,2] row_mask:0xf bank_mask:0xf
	s_and_saveexec_b64 s[20:21], vcc
	s_cbranch_execz .LBB0_1302
	s_waitcnt lgkmcnt(0)
	v_cvt_pk_bf16_f32 v13, v13, v17
	global_store_dword v[18:19], v13, off offset:384
.LBB0_1302:
	s_or_b64 exec, exec, s[20:21]
	v_mul_f32_e32 v12, v23, v12
	s_nop 1
	v_mov_b32_dpp v13, v12 quad_perm:[1,0,3,2] row_mask:0xf bank_mask:0xf
	s_and_saveexec_b64 s[20:21], vcc
	s_cbranch_execz .LBB0_1304
	s_waitcnt lgkmcnt(0)
	v_cvt_pk_bf16_f32 v12, v12, v13
	global_store_dword v[18:19], v12, off offset:448
.LBB0_1304:
	s_or_b64 exec, exec, s[20:21]
	v_rcp_f32_e32 v12, v14
	s_waitcnt lgkmcnt(0)
	v_mul_f32_e32 v13, v72, v12
	s_nop 1
	v_mov_b32_dpp v14, v13 quad_perm:[1,0,3,2] row_mask:0xf bank_mask:0xf
	s_and_saveexec_b64 s[20:21], vcc
	s_cbranch_execz .LBB0_1306
	s_waitcnt lgkmcnt(0)
	v_cvt_pk_bf16_f32 v13, v13, v14
	global_store_dword v[18:19], v13, off offset:512
.LBB0_1306:
	s_or_b64 exec, exec, s[20:21]
	v_mul_f32_e32 v13, v56, v12
	s_waitcnt lgkmcnt(0)
	s_nop 1
	v_mov_b32_dpp v14, v13 quad_perm:[1,0,3,2] row_mask:0xf bank_mask:0xf
	s_and_saveexec_b64 s[20:21], vcc
	s_cbranch_execz .LBB0_1308
	s_waitcnt lgkmcnt(0)
	v_cvt_pk_bf16_f32 v13, v13, v14
	global_store_dword v[18:19], v13, off offset:576
.LBB0_1308:
	s_or_b64 exec, exec, s[20:21]
	v_mul_f32_e32 v13, v40, v12
	s_waitcnt lgkmcnt(0)
	s_nop 1
	v_mov_b32_dpp v14, v13 quad_perm:[1,0,3,2] row_mask:0xf bank_mask:0xf
	s_and_saveexec_b64 s[20:21], vcc
	s_cbranch_execz .LBB0_1310
	s_waitcnt lgkmcnt(0)
	v_cvt_pk_bf16_f32 v13, v13, v14
	global_store_dword v[18:19], v13, off offset:640
.LBB0_1310:
	s_or_b64 exec, exec, s[20:21]
	v_mul_f32_e32 v12, v24, v12
	s_nop 1
	v_mov_b32_dpp v13, v12 quad_perm:[1,0,3,2] row_mask:0xf bank_mask:0xf
	s_and_saveexec_b64 s[20:21], vcc
	s_cbranch_execz .LBB0_1312
	s_waitcnt lgkmcnt(0)
	v_cvt_pk_bf16_f32 v12, v12, v13
	global_store_dword v[18:19], v12, off offset:704
.LBB0_1312:
	s_or_b64 exec, exec, s[20:21]
	v_rcp_f32_e32 v12, v15
	s_waitcnt lgkmcnt(0)
	v_mul_f32_e32 v13, v73, v12
	s_nop 1
	v_mov_b32_dpp v14, v13 quad_perm:[1,0,3,2] row_mask:0xf bank_mask:0xf
	s_and_saveexec_b64 s[20:21], vcc
	s_cbranch_execz .LBB0_1314
	s_waitcnt lgkmcnt(0)
	v_cvt_pk_bf16_f32 v13, v13, v14
	global_store_dword v[18:19], v13, off offset:768
.LBB0_1314:
	s_or_b64 exec, exec, s[20:21]
	v_mul_f32_e32 v13, v57, v12
	s_waitcnt lgkmcnt(0)
	s_nop 1
	v_mov_b32_dpp v14, v13 quad_perm:[1,0,3,2] row_mask:0xf bank_mask:0xf
	s_and_saveexec_b64 s[20:21], vcc
	s_cbranch_execz .LBB0_1316
	s_waitcnt lgkmcnt(0)
	v_cvt_pk_bf16_f32 v13, v13, v14
	global_store_dword v[18:19], v13, off offset:832
; __device__ __forceinline__ unsigned cvtpk(float lo, float hi) { unsigned r; asm volatile("v_cvt_pk_bf16_f32 %0, %1, %2" : "=v"(r) : "v"(lo), "v"(hi)); return r; }
; __device__ __forceinline__ int crow(int r, int hi) { return (r & 3) + 8 * (r >> 2) + 4 * hi; }
; template <int MODE>
; __device__ __forceinline__ void block(const Ref& cur, const Ref& nxt, char* lds, Seam& S) {
;     ...
;     for (int r = 0; r < 16; ++r) { bf16_t* orow = cur.O + qrow_off<MODE>(wid * QBLK + crow(r, hie));
; #pragma unroll
;         for (int d0 = 0; d0 < 4; ++d0) { const float v = o[d0][r] * rli[r];
;             const float vn = __shfl_xor(v, 1);
;             if ((r32e & 1) == 0) *(unsigned*)(orow + d0 * 32 + r32e) = cvtpk(v, vn); } }
.LBB0_1316:
	s_or_b64 exec, exec, s[20:21]
	v_mul_f32_e32 v13, v41, v12
	s_waitcnt lgkmcnt(0)
	s_nop 1
	v_mov_b32_dpp v14, v13 quad_perm:[1,0,3,2] row_mask:0xf bank_mask:0xf
	s_and_saveexec_b64 s[20:21], vcc
	s_cbranch_execz .LBB0_1318
	s_waitcnt lgkmcnt(0)
	v_cvt_pk_bf16_f32 v13, v13, v14
	global_store_dword v[18:19], v13, off offset:896
.LBB0_1318:
	s_or_b64 exec, exec, s[20:21]
	v_mul_f32_e32 v12, v25, v12
	s_nop 1
	v_mov_b32_dpp v13, v12 quad_perm:[1,0,3,2] row_mask:0xf bank_mask:0xf
	s_and_saveexec_b64 s[20:21], vcc
	s_cbranch_execz .LBB0_1320
	s_waitcnt lgkmcnt(0)
	v_cvt_pk_bf16_f32 v12, v12, v13
	global_store_dword v[18:19], v12, off offset:960
.LBB0_1320:
	s_or_b64 exec, exec, s[20:21]
	v_rcp_f32_e32 v8, v8
	s_or_b32 s20, s6, 2
	s_mov_b32 s21, s7
	s_lshl_b64 s[20:21], s[20:21], 12
	s_waitcnt lgkmcnt(1)
	v_mul_f32_e32 v14, v74, v8
	s_nop 1
	v_mov_b32_dpp v15, v14 quad_perm:[1,0,3,2] row_mask:0xf bank_mask:0xf
	s_add_u32 s20, s18, s20
	s_addc_u32 s21, s19, s21
	v_mov_b32_e32 v17, v3
	s_waitcnt lgkmcnt(1)
	v_lshl_add_u64 v[12:13], s[20:21], 0, v[16:17]
	v_lshl_add_u64 v[12:13], v[12:13], 0, v[2:3]
	s_and_saveexec_b64 s[20:21], vcc
	s_cbranch_execz .LBB0_1322
	s_waitcnt lgkmcnt(0)
	v_cvt_pk_bf16_f32 v14, v14, v15
	global_store_dword v[12:13], v14, off
.LBB0_1322:
	s_or_b64 exec, exec, s[20:21]
	v_mul_f32_e32 v14, v58, v8
	s_waitcnt lgkmcnt(0)
	s_nop 1
	v_mov_b32_dpp v15, v14 quad_perm:[1,0,3,2] row_mask:0xf bank_mask:0xf
	s_and_saveexec_b64 s[20:21], vcc
	s_cbranch_execz .LBB0_1324
	s_waitcnt lgkmcnt(0)
	v_cvt_pk_bf16_f32 v14, v14, v15
	global_store_dword v[12:13], v14, off offset:64
.LBB0_1324:
	s_or_b64 exec, exec, s[20:21]
	v_mul_f32_e32 v14, v42, v8
	s_waitcnt lgkmcnt(0)
	s_nop 1
	v_mov_b32_dpp v15, v14 quad_perm:[1,0,3,2] row_mask:0xf bank_mask:0xf
	s_and_saveexec_b64 s[20:21], vcc
	s_cbranch_execz .LBB0_1326
	s_waitcnt lgkmcnt(0)
	v_cvt_pk_bf16_f32 v14, v14, v15
	global_store_dword v[12:13], v14, off offset:128
.LBB0_1326:
	s_or_b64 exec, exec, s[20:21]
	v_mul_f32_e32 v8, v26, v8
	s_nop 1
	v_mov_b32_dpp v14, v8 quad_perm:[1,0,3,2] row_mask:0xf bank_mask:0xf
	s_and_saveexec_b64 s[20:21], vcc
	s_cbranch_execz .LBB0_1328
	s_waitcnt lgkmcnt(0)
	v_cvt_pk_bf16_f32 v8, v8, v14
	global_store_dword v[12:13], v8, off offset:192
.LBB0_1328:
	s_or_b64 exec, exec, s[20:21]
	v_rcp_f32_e32 v8, v9
	s_nop 0
	v_mul_f32_e32 v9, v75, v8
	s_waitcnt lgkmcnt(0)
	s_nop 1
	v_mov_b32_dpp v14, v9 quad_perm:[1,0,3,2] row_mask:0xf bank_mask:0xf
	s_and_saveexec_b64 s[20:21], vcc
	s_cbranch_execz .LBB0_1330
	s_waitcnt lgkmcnt(0)
	v_cvt_pk_bf16_f32 v9, v9, v14
	global_store_dword v[12:13], v9, off offset:256
.LBB0_1330:
	s_or_b64 exec, exec, s[20:21]
	v_mul_f32_e32 v9, v59, v8
	s_waitcnt lgkmcnt(0)
	s_nop 1
	v_mov_b32_dpp v14, v9 quad_perm:[1,0,3,2] row_mask:0xf bank_mask:0xf
	s_and_saveexec_b64 s[20:21], vcc
	s_cbranch_execz .LBB0_1332
	s_waitcnt lgkmcnt(0)
	v_cvt_pk_bf16_f32 v9, v9, v14
	global_store_dword v[12:13], v9, off offset:320
.LBB0_1332:
	s_or_b64 exec, exec, s[20:21]
	v_mul_f32_e32 v9, v43, v8
	s_waitcnt lgkmcnt(0)
	s_nop 1
	v_mov_b32_dpp v14, v9 quad_perm:[1,0,3,2] row_mask:0xf bank_mask:0xf
	s_and_saveexec_b64 s[20:21], vcc
	s_cbranch_execz .LBB0_1334
	s_waitcnt lgkmcnt(0)
	v_cvt_pk_bf16_f32 v9, v9, v14
	global_store_dword v[12:13], v9, off offset:384
.LBB0_1334:
	s_or_b64 exec, exec, s[20:21]
	v_mul_f32_e32 v8, v27, v8
	s_nop 1
	v_mov_b32_dpp v9, v8 quad_perm:[1,0,3,2] row_mask:0xf bank_mask:0xf
	s_and_saveexec_b64 s[20:21], vcc
	s_cbranch_execz .LBB0_1336
	s_waitcnt lgkmcnt(0)
	v_cvt_pk_bf16_f32 v8, v8, v9
	global_store_dword v[12:13], v8, off offset:448
.LBB0_1336:
	s_or_b64 exec, exec, s[20:21]
	v_rcp_f32_e32 v8, v10
	s_waitcnt lgkmcnt(0)
	v_mul_f32_e32 v9, v76, v8
	s_nop 1
	v_mov_b32_dpp v10, v9 quad_perm:[1,0,3,2] row_mask:0xf bank_mask:0xf
	s_and_saveexec_b64 s[20:21], vcc
	s_cbranch_execz .LBB0_1338
	s_waitcnt lgkmcnt(0)
	v_cvt_pk_bf16_f32 v9, v9, v10
	global_store_dword v[12:13], v9, off offset:512
.LBB0_1338:
	s_or_b64 exec, exec, s[20:21]
	v_mul_f32_e32 v9, v60, v8
	s_waitcnt lgkmcnt(0)
	s_nop 1
	v_mov_b32_dpp v10, v9 quad_perm:[1,0,3,2] row_mask:0xf bank_mask:0xf
	s_and_saveexec_b64 s[20:21], vcc
	s_cbranch_execz .LBB0_1340
	s_waitcnt lgkmcnt(0)
	v_cvt_pk_bf16_f32 v9, v9, v10
	global_store_dword v[12:13], v9, off offset:576
.LBB0_1340:
	s_or_b64 exec, exec, s[20:21]
	v_mul_f32_e32 v9, v44, v8
	s_waitcnt lgkmcnt(0)
	s_nop 1
	v_mov_b32_dpp v10, v9 quad_perm:[1,0,3,2] row_mask:0xf bank_mask:0xf
	s_and_saveexec_b64 s[20:21], vcc
	s_cbranch_execz .LBB0_1342
	s_waitcnt lgkmcnt(0)
	v_cvt_pk_bf16_f32 v9, v9, v10
	global_store_dword v[12:13], v9, off offset:640
.LBB0_1342:
	s_or_b64 exec, exec, s[20:21]
	v_mul_f32_e32 v8, v28, v8
	s_nop 1
	v_mov_b32_dpp v9, v8 quad_perm:[1,0,3,2] row_mask:0xf bank_mask:0xf
	s_and_saveexec_b64 s[20:21], vcc
	s_cbranch_execz .LBB0_1344
	s_waitcnt lgkmcnt(0)
	v_cvt_pk_bf16_f32 v8, v8, v9
	global_store_dword v[12:13], v8, off offset:704
.LBB0_1344:
	s_or_b64 exec, exec, s[20:21]
	v_rcp_f32_e32 v8, v11
	s_waitcnt lgkmcnt(0)
	v_mul_f32_e32 v9, v77, v8
	s_nop 1
	v_mov_b32_dpp v10, v9 quad_perm:[1,0,3,2] row_mask:0xf bank_mask:0xf
	s_and_saveexec_b64 s[20:21], vcc
	s_cbranch_execz .LBB0_1346
	s_waitcnt lgkmcnt(0)
	v_cvt_pk_bf16_f32 v9, v9, v10
	global_store_dword v[12:13], v9, off offset:768
.LBB0_1346:
	s_or_b64 exec, exec, s[20:21]
	v_mul_f32_e32 v9, v61, v8
	s_waitcnt lgkmcnt(0)
	s_nop 1
	v_mov_b32_dpp v10, v9 quad_perm:[1,0,3,2] row_mask:0xf bank_mask:0xf
	s_and_saveexec_b64 s[20:21], vcc
	s_cbranch_execz .LBB0_1348
	s_waitcnt lgkmcnt(0)
	v_cvt_pk_bf16_f32 v9, v9, v10
	global_store_dword v[12:13], v9, off offset:832
; __device__ __forceinline__ unsigned cvtpk(float lo, float hi) { unsigned r; asm volatile("v_cvt_pk_bf16_f32 %0, %1, %2" : "=v"(r) : "v"(lo), "v"(hi)); return r; }
; __device__ __forceinline__ int crow(int r, int hi) { return (r & 3) + 8 * (r >> 2) + 4 * hi; }
; template <int MODE>
; __device__ __forceinline__ void block(const Ref& cur, const Ref& nxt, char* lds, Seam& S) {
;     ...
;     for (int r = 0; r < 16; ++r) { bf16_t* orow = cur.O + qrow_off<MODE>(wid * QBLK + crow(r, hie));
; #pragma unroll
;         for (int d0 = 0; d0 < 4; ++d0) { const float v = o[d0][r] * rli[r];
;             const float vn = __shfl_xor(v, 1);
;             if ((r32e & 1) == 0) *(unsigned*)(orow + d0 * 32 + r32e) = cvtpk(v, vn); } }
.LBB0_1348:
	s_or_b64 exec, exec, s[20:21]
	v_mul_f32_e32 v9, v45, v8
	s_waitcnt lgkmcnt(0)
	s_nop 1
	v_mov_b32_dpp v10, v9 quad_perm:[1,0,3,2] row_mask:0xf bank_mask:0xf
	s_and_saveexec_b64 s[20:21], vcc
	s_cbranch_execz .LBB0_1350
	s_waitcnt lgkmcnt(0)
	v_cvt_pk_bf16_f32 v9, v9, v10
	global_store_dword v[12:13], v9, off offset:896
.LBB0_1350:
	s_or_b64 exec, exec, s[20:21]
	v_mul_f32_e32 v8, v29, v8
	s_nop 1
	v_mov_b32_dpp v9, v8 quad_perm:[1,0,3,2] row_mask:0xf bank_mask:0xf
	s_and_saveexec_b64 s[20:21], vcc
	s_cbranch_execz .LBB0_1352
	s_waitcnt lgkmcnt(0)
	v_cvt_pk_bf16_f32 v8, v8, v9
	global_store_dword v[12:13], v8, off offset:960
.LBB0_1352:
	s_or_b64 exec, exec, s[20:21]
	v_rcp_f32_e32 v4, v4
	s_or_b32 s6, s6, 3
	s_lshl_b64 s[20:21], s[6:7], 12
	s_add_u32 s18, s18, s20
	s_waitcnt lgkmcnt(1)
	v_mul_f32_e32 v10, v78, v4
	s_nop 1
	v_mov_b32_dpp v11, v10 quad_perm:[1,0,3,2] row_mask:0xf bank_mask:0xf
	s_addc_u32 s19, s19, s21
	v_mov_b32_e32 v17, v3
	s_waitcnt lgkmcnt(1)
	v_lshl_add_u64 v[8:9], s[18:19], 0, v[16:17]
	v_lshl_add_u64 v[8:9], v[8:9], 0, v[2:3]
	s_and_saveexec_b64 s[18:19], vcc
	s_cbranch_execz .LBB0_1354
	s_waitcnt lgkmcnt(0)
	v_cvt_pk_bf16_f32 v2, v10, v11
	global_store_dword v[8:9], v2, off
.LBB0_1354:
	s_or_b64 exec, exec, s[18:19]
	v_mul_f32_e32 v2, v62, v4
	s_nop 1
	v_mov_b32_dpp v10, v2 quad_perm:[1,0,3,2] row_mask:0xf bank_mask:0xf
	s_and_saveexec_b64 s[18:19], vcc
	s_cbranch_execz .LBB0_1356
	s_waitcnt lgkmcnt(0)
	v_cvt_pk_bf16_f32 v2, v2, v10
	global_store_dword v[8:9], v2, off offset:64
.LBB0_1356:
	s_or_b64 exec, exec, s[18:19]
	v_mul_f32_e32 v2, v46, v4
	s_waitcnt lgkmcnt(0)
	s_nop 1
	v_mov_b32_dpp v10, v2 quad_perm:[1,0,3,2] row_mask:0xf bank_mask:0xf
	s_and_saveexec_b64 s[18:19], vcc
	s_cbranch_execz .LBB0_1358
	s_waitcnt lgkmcnt(0)
	v_cvt_pk_bf16_f32 v2, v2, v10
	global_store_dword v[8:9], v2, off offset:128
.LBB0_1358:
	s_or_b64 exec, exec, s[18:19]
	v_mul_f32_e32 v2, v30, v4
	s_nop 1
	v_mov_b32_dpp v4, v2 quad_perm:[1,0,3,2] row_mask:0xf bank_mask:0xf
	s_and_saveexec_b64 s[18:19], vcc
	s_cbranch_execz .LBB0_1360
	s_waitcnt lgkmcnt(0)
	v_cvt_pk_bf16_f32 v2, v2, v4
	global_store_dword v[8:9], v2, off offset:192
.LBB0_1360:
	s_or_b64 exec, exec, s[18:19]
	v_rcp_f32_e32 v2, v5
	s_waitcnt lgkmcnt(0)
	v_mul_f32_e32 v4, v79, v2
	s_nop 1
	v_mov_b32_dpp v5, v4 quad_perm:[1,0,3,2] row_mask:0xf bank_mask:0xf
	s_and_saveexec_b64 s[18:19], vcc
	s_cbranch_execz .LBB0_1362
	s_waitcnt lgkmcnt(0)
	v_cvt_pk_bf16_f32 v4, v4, v5
	global_store_dword v[8:9], v4, off offset:256
.LBB0_1362:
	s_or_b64 exec, exec, s[18:19]
	v_mul_f32_e32 v4, v63, v2
	s_waitcnt lgkmcnt(0)
	s_nop 1
	v_mov_b32_dpp v5, v4 quad_perm:[1,0,3,2] row_mask:0xf bank_mask:0xf
	s_and_saveexec_b64 s[18:19], vcc
	s_cbranch_execz .LBB0_1364
	s_waitcnt lgkmcnt(0)
	v_cvt_pk_bf16_f32 v4, v4, v5
	global_store_dword v[8:9], v4, off offset:320
.LBB0_1364:
	s_or_b64 exec, exec, s[18:19]
	v_mul_f32_e32 v4, v47, v2
	s_waitcnt lgkmcnt(0)
	s_nop 1
	v_mov_b32_dpp v5, v4 quad_perm:[1,0,3,2] row_mask:0xf bank_mask:0xf
	s_and_saveexec_b64 s[18:19], vcc
	s_cbranch_execz .LBB0_1366
	s_waitcnt lgkmcnt(0)
	v_cvt_pk_bf16_f32 v4, v4, v5
	global_store_dword v[8:9], v4, off offset:384
.LBB0_1366:
	s_or_b64 exec, exec, s[18:19]
	v_mul_f32_e32 v2, v31, v2
	s_nop 1
	v_mov_b32_dpp v4, v2 quad_perm:[1,0,3,2] row_mask:0xf bank_mask:0xf
	s_and_saveexec_b64 s[18:19], vcc
	s_cbranch_execz .LBB0_1368
	s_waitcnt lgkmcnt(0)
	v_cvt_pk_bf16_f32 v2, v2, v4
	global_store_dword v[8:9], v2, off offset:448
.LBB0_1368:
	s_or_b64 exec, exec, s[18:19]
	v_rcp_f32_e32 v2, v6
	s_waitcnt lgkmcnt(0)
	v_mul_f32_e32 v4, v80, v2
	s_nop 1
	v_mov_b32_dpp v5, v4 quad_perm:[1,0,3,2] row_mask:0xf bank_mask:0xf
	s_and_saveexec_b64 s[18:19], vcc
	s_cbranch_execz .LBB0_1370
	s_waitcnt lgkmcnt(0)
	v_cvt_pk_bf16_f32 v4, v4, v5
	global_store_dword v[8:9], v4, off offset:512
.LBB0_1370:
	s_or_b64 exec, exec, s[18:19]
	v_mul_f32_e32 v4, v64, v2
	s_waitcnt lgkmcnt(0)
	s_nop 1
	v_mov_b32_dpp v5, v4 quad_perm:[1,0,3,2] row_mask:0xf bank_mask:0xf
	s_and_saveexec_b64 s[18:19], vcc
	s_cbranch_execz .LBB0_1372
	s_waitcnt lgkmcnt(0)
	v_cvt_pk_bf16_f32 v4, v4, v5
	global_store_dword v[8:9], v4, off offset:576
.LBB0_1372:
	s_or_b64 exec, exec, s[18:19]
	v_mul_f32_e32 v4, v48, v2
	s_waitcnt lgkmcnt(0)
	s_nop 1
	v_mov_b32_dpp v5, v4 quad_perm:[1,0,3,2] row_mask:0xf bank_mask:0xf
	s_and_saveexec_b64 s[18:19], vcc
	s_cbranch_execz .LBB0_1374
	s_waitcnt lgkmcnt(0)
	v_cvt_pk_bf16_f32 v4, v4, v5
	global_store_dword v[8:9], v4, off offset:640
.LBB0_1374:
	s_or_b64 exec, exec, s[18:19]
	v_mul_f32_e32 v2, v32, v2
	s_nop 1
	v_mov_b32_dpp v4, v2 quad_perm:[1,0,3,2] row_mask:0xf bank_mask:0xf
	s_and_saveexec_b64 s[18:19], vcc
	s_cbranch_execz .LBB0_1376
	s_waitcnt lgkmcnt(0)
	v_cvt_pk_bf16_f32 v2, v2, v4
	global_store_dword v[8:9], v2, off offset:704
.LBB0_1376:
	s_or_b64 exec, exec, s[18:19]
	v_rcp_f32_e32 v2, v7
	s_waitcnt lgkmcnt(0)
	v_mul_f32_e32 v4, v81, v2
	s_nop 1
	v_mov_b32_dpp v5, v4 quad_perm:[1,0,3,2] row_mask:0xf bank_mask:0xf
	s_and_saveexec_b64 s[18:19], vcc
	s_cbranch_execz .LBB0_1378
	s_waitcnt lgkmcnt(0)
	v_cvt_pk_bf16_f32 v4, v4, v5
	global_store_dword v[8:9], v4, off offset:768
.LBB0_1378:
	s_or_b64 exec, exec, s[18:19]
	v_mul_f32_e32 v4, v65, v2
	s_waitcnt lgkmcnt(0)
	s_nop 1
	v_mov_b32_dpp v5, v4 quad_perm:[1,0,3,2] row_mask:0xf bank_mask:0xf
	s_and_saveexec_b64 s[18:19], vcc
	s_cbranch_execz .LBB0_1380
	s_waitcnt lgkmcnt(0)
	v_cvt_pk_bf16_f32 v4, v4, v5
	global_store_dword v[8:9], v4, off offset:832
.LBB0_1380:
	s_or_b64 exec, exec, s[18:19]
	v_mul_f32_e32 v4, v49, v2
	s_waitcnt lgkmcnt(0)
	s_nop 1
	v_mov_b32_dpp v5, v4 quad_perm:[1,0,3,2] row_mask:0xf bank_mask:0xf
	s_and_saveexec_b64 s[18:19], vcc
	s_cbranch_execz .LBB0_1382
	s_waitcnt lgkmcnt(0)
	v_cvt_pk_bf16_f32 v4, v4, v5
	global_store_dword v[8:9], v4, off offset:896
.LBB0_1382:
	s_or_b64 exec, exec, s[18:19]
	v_mul_f32_e32 v2, v33, v2
	s_nop 1
	v_mov_b32_dpp v1, v2 quad_perm:[1,0,3,2] row_mask:0xf bank_mask:0xf
	s_and_saveexec_b64 s[18:19], vcc
	s_cbranch_execz .LBB0_1216
	s_waitcnt lgkmcnt(0)
	v_cvt_pk_bf16_f32 v1, v2, v1
	global_store_dword v[8:9], v1, off offset:960
	s_branch .LBB0_1216
